# NSA tile: all eight K fragments read up front into idle registers, QK MFMAs back to back with counted waits
# baseline (speedup 1.0000x reference)
; DEV f32x16 mfma32(bf16x8 a, bf16x8 b, f32x16 c) { return __builtin_amdgcn_mfma_f32_32x32x16_bf16(a, b, c, 0, 0, 0); }
; DEV void att_tile64(AttAcc& A, const f32x16& s0, const f32x16& s1, float qs, float slope2, int dt, float lane_bias, bool masked, int wlim,
;                     const bf16_t* vt, size_t vstride) {
;   const float sb = slope2 * (float)dt + lane_bias;
;   float sc[32];
; #pragma unroll
;   for (int i = 0; i < 16; ++i) {
;     const int c = (i & 7) + 16 * (i >> 3);
;     sc[i] = fmaf(s0[i], qs, fmaf(slope2, (float)c, -sb));
;     sc[16 + i] = fmaf(s1[i], qs, fmaf(slope2, (float)(c + 32), -sb));
;   }
; __device__ void nsa_item(const Params& P, int l, int item, char* smem) {
;     ...
;         const bf16_t* buf = kvs + (i & 1) * 9216;
;         f32x16 s0, s1;
; #pragma unroll
;         for (int e = 0; e < 16; ++e) { s0[e] = 0.f; s1[e] = 0.f; }
;         {
;           const bf16_t* kl = buf + q * 72 + hk * 8;
; #pragma unroll
;           for (int ks = 0; ks < 4; ++ks) {
;             s0 = mfma32(*(const bf16x8*)(kl + ks * 16), qf[ks], s0);
;             s1 = mfma32(*(const bf16x8*)(kl + 32 * 72 + ks * 16), qf[ks], s1);
;           }
;         }
;         float lane_bias = 0.f;
;         if (br == 0) { const bool selj = (selmask >> (kb >> 6)) & 1ull; lane_bias = selj ? 0.f : 1e30f; }
;         const bool masked = (kb + 63 > t0) || (br == 1 && kb <= t0 - 481);
;         att_tile64(A, s0, s1, qs2, slope2, t - kb - 8 * hk, lane_bias, masked, wlim, buf + 4608 + q * 72 + 8 * hk, 72);
.LBB0_184:
	s_sub_i32 s39, s63, 63
	s_bitcmp1_b32 s2, 0
	s_cselect_b32 s48, 0x4800, 0
	v_add_u32_e32 v159, s48, v153
	ds_read_b128 v[180:183], v159 offset:34816
	ds_read_b128 v[184:187], v159 offset:39424
	ds_read_b128 v[188:191], v159 offset:34848
	ds_read_b128 v[192:195], v159 offset:39456
	ds_read_b128 v[196:199], v159 offset:34880
	ds_read_b128 v[228:231], v159 offset:39488
	ds_read_b128 v[232:235], v159 offset:34912
	ds_read_b128 v[236:239], v159 offset:39520
	s_ashr_i32 s48, s39, 6
	s_lshl_b64 s[48:49], 1, s48
	s_waitcnt lgkmcnt(7)
	v_mfma_f32_32x32x16_bf16 v[48:63], v[180:183], v[64:67], 0
	s_waitcnt lgkmcnt(6)
	v_mfma_f32_32x32x16_bf16 v[32:47], v[184:187], v[64:67], 0
	s_waitcnt lgkmcnt(5)
	v_mfma_f32_32x32x16_bf16 v[48:63], v[188:191], v[68:71], v[48:63]
	s_waitcnt lgkmcnt(4)
	v_mfma_f32_32x32x16_bf16 v[32:47], v[192:195], v[68:71], v[32:47]
	s_waitcnt lgkmcnt(3)
	v_mfma_f32_32x32x16_bf16 v[48:63], v[196:199], v[72:75], v[48:63]
	s_waitcnt lgkmcnt(2)
	v_mfma_f32_32x32x16_bf16 v[32:47], v[228:231], v[72:75], v[32:47]
	s_waitcnt lgkmcnt(1)
	v_mfma_f32_32x32x16_bf16 v[48:63], v[232:235], v[76:79], v[48:63]
	s_waitcnt lgkmcnt(0)
	v_mfma_f32_32x32x16_bf16 v[32:47], v[236:239], v[76:79], v[32:47]
	v_and_b32_e32 v117, s49, v97
	v_and_b32_e32 v116, s48, v96
	v_cmp_eq_u64_e32 vcc, 0, v[116:117]
	v_cvt_f32_i32_e32 v116, v157
	s_and_b64 vcc, s[42:43], vcc
	v_cndmask_b32_e32 v160, 0, v218, vcc
	s_cmp_gt_i32 s63, s50
	v_fmac_f32_e32 v160, v100, v116
	v_fma_f32 v116, v100, 0, -v160
	v_sub_f32_e32 v117, v100, v160
	v_pk_fma_f32 v[118:119], v[48:49], s[36:37], v[116:117] op_sel_hi:[1,0,1]
	v_pk_fma_f32 v[48:49], v[100:101], s[34:35], v[160:161] op_sel_hi:[1,1,0] neg_lo:[0,0,1] neg_hi:[0,0,1]
	s_cselect_b64 s[48:49], -1, 0
	v_pk_fma_f32 v[116:117], v[32:33], s[36:37], v[48:49] op_sel_hi:[1,0,1]
	v_pk_fma_f32 v[32:33], v[100:101], s[12:13], v[160:161] op_sel_hi:[1,1,0] neg_lo:[0,0,1] neg_hi:[0,0,1]
	s_cmp_le_i32 s39, s65
	v_pk_fma_f32 v[120:121], v[50:51], s[36:37], v[32:33] op_sel_hi:[1,0,1]
	v_pk_fma_f32 v[32:33], v[100:101], s[8:9], v[160:161] op_sel_hi:[1,1,0] neg_lo:[0,0,1] neg_hi:[0,0,1]
	s_cselect_b64 vcc, -1, 0
	v_pk_fma_f32 v[50:51], v[34:35], s[36:37], v[32:33] op_sel_hi:[1,0,1]
	v_pk_fma_f32 v[32:33], v[100:101], s[10:11], v[160:161] op_sel_hi:[1,1,0] neg_lo:[0,0,1] neg_hi:[0,0,1]
	s_and_b64 vcc, s[44:45], vcc
	v_pk_fma_f32 v[52:53], v[52:53], s[36:37], v[32:33] op_sel_hi:[1,0,1]
	v_pk_fma_f32 v[32:33], v[100:101], s[14:15], v[160:161] op_sel_hi:[1,1,0] neg_lo:[0,0,1] neg_hi:[0,0,1]
	s_or_b64 s[48:49], s[48:49], vcc
	v_pk_fma_f32 v[48:49], v[36:37], s[36:37], v[32:33] op_sel_hi:[1,0,1]
	v_pk_fma_f32 v[32:33], v[100:101], s[16:17], v[160:161] op_sel_hi:[1,1,0] neg_lo:[0,0,1] neg_hi:[0,0,1]
	s_andn2_b64 vcc, exec, s[48:49]
	v_pk_fma_f32 v[54:55], v[54:55], s[36:37], v[32:33] op_sel_hi:[1,0,1]
	v_pk_fma_f32 v[32:33], v[100:101], s[18:19], v[160:161] op_sel_hi:[1,1,0] neg_lo:[0,0,1] neg_hi:[0,0,1]
	s_nop 0
	v_pk_fma_f32 v[34:35], v[38:39], s[36:37], v[32:33] op_sel_hi:[1,0,1]
	v_pk_fma_f32 v[32:33], v[100:101], s[20:21], v[160:161] op_sel_hi:[1,1,0] neg_lo:[0,0,1] neg_hi:[0,0,1]
	s_nop 0
	v_pk_fma_f32 v[56:57], v[56:57], s[36:37], v[32:33] op_sel_hi:[1,0,1]
	v_pk_fma_f32 v[32:33], v[100:101], s[22:23], v[160:161] op_sel_hi:[1,1,0] neg_lo:[0,0,1] neg_hi:[0,0,1]
	s_nop 0
	v_pk_fma_f32 v[36:37], v[40:41], s[36:37], v[32:33] op_sel_hi:[1,0,1]
	v_pk_fma_f32 v[32:33], v[100:101], s[84:85], v[160:161] op_sel_hi:[1,1,0] neg_lo:[0,0,1] neg_hi:[0,0,1]
	s_nop 0
	v_pk_fma_f32 v[58:59], v[58:59], s[36:37], v[32:33] op_sel_hi:[1,0,1]
	v_pk_fma_f32 v[32:33], v[100:101], s[86:87], v[160:161] op_sel_hi:[1,1,0] neg_lo:[0,0,1] neg_hi:[0,0,1]
	s_nop 0
	v_pk_fma_f32 v[38:39], v[42:43], s[36:37], v[32:33] op_sel_hi:[1,0,1]
	v_pk_fma_f32 v[32:33], v[100:101], s[88:89], v[160:161] op_sel_hi:[1,1,0] neg_lo:[0,0,1] neg_hi:[0,0,1]
	s_nop 0
	v_pk_fma_f32 v[42:43], v[60:61], s[36:37], v[32:33] op_sel_hi:[1,0,1]
	v_pk_fma_f32 v[32:33], v[100:101], s[90:91], v[160:161] op_sel_hi:[1,1,0] neg_lo:[0,0,1] neg_hi:[0,0,1]
	s_nop 0
	v_pk_fma_f32 v[40:41], v[44:45], s[36:37], v[32:33] op_sel_hi:[1,0,1]
	v_pk_fma_f32 v[32:33], v[100:101], s[92:93], v[160:161] op_sel_hi:[1,1,0] neg_lo:[0,0,1] neg_hi:[0,0,1]
	s_nop 0
	v_pk_fma_f32 v[44:45], v[62:63], s[36:37], v[32:33] op_sel_hi:[1,0,1]
	v_pk_fma_f32 v[32:33], v[100:101], s[94:95], v[160:161] op_sel_hi:[1,1,0] neg_lo:[0,0,1] neg_hi:[0,0,1]
	s_nop 0
	v_pk_fma_f32 v[32:33], v[46:47], s[36:37], v[32:33] op_sel_hi:[1,0,1]
	s_cbranch_vccnz .LBB0_186
; DEV void att_tile64(AttAcc& A, const f32x16& s0, const f32x16& s1, float qs, float slope2, int dt, float lane_bias, bool masked, int wlim,
;                     const bf16_t* vt, size_t vstride) {
;     ...
;   if (masked) {
; #pragma unroll
;     for (int i = 0; i < 32; ++i) {
;       const int c = (i & 7) + 16 * ((i & 15) >> 3) + 32 * (i >> 4);
;       const int di = dt - c;
;       sc[i] = (di >= 0 && di < wlim) ? sc[i] : -3.0e38f;
;     }
;   }
	v_add_u32_e32 v46, -1, v157
	v_cmp_gt_u32_e32 vcc, s61, v46
	v_add_u32_e32 v46, -3, v157
	v_add_u32_e32 v47, -2, v157
	v_cndmask_b32_e32 v119, v219, v119, vcc
	v_cmp_gt_u32_e32 vcc, s60, v157
	s_nop 1
	v_cndmask_b32_e32 v118, v219, v118, vcc
	v_cmp_gt_u32_e32 vcc, s61, v46
	v_add_u32_e32 v46, -5, v157
	s_nop 0
	v_cndmask_b32_e32 v121, v219, v121, vcc
	v_cmp_gt_u32_e32 vcc, s60, v47
	v_add_u32_e32 v47, -4, v157
	s_nop 0
	v_cndmask_b32_e32 v120, v219, v120, vcc
	v_cmp_gt_u32_e32 vcc, s61, v46
	v_add_u32_e32 v46, -7, v157
	s_nop 0
	v_cndmask_b32_e32 v53, v219, v53, vcc
	v_cmp_gt_u32_e32 vcc, s60, v47
	v_add_u32_e32 v47, -6, v157
	s_nop 0
	v_cndmask_b32_e32 v52, v219, v52, vcc
	v_cmp_gt_u32_e32 vcc, s61, v46
	v_add_u32_e32 v46, -16, v157
	s_nop 0
	v_cndmask_b32_e32 v55, v219, v55, vcc
	v_cmp_gt_u32_e32 vcc, s60, v47
	v_subrev_u32_e32 v47, 17, v157
	s_nop 0
	v_cndmask_b32_e32 v54, v219, v54, vcc
	v_cmp_gt_u32_e32 vcc, s61, v47
	v_subrev_u32_e32 v47, 18, v157
	s_nop 0
	v_cndmask_b32_e32 v57, v219, v57, vcc
	v_cmp_gt_u32_e32 vcc, s60, v46
	v_subrev_u32_e32 v46, 19, v157
	s_nop 0
	v_cndmask_b32_e32 v56, v219, v56, vcc
	v_cmp_gt_u32_e32 vcc, s61, v46
	v_subrev_u32_e32 v46, 21, v157
	s_nop 0
	v_cndmask_b32_e32 v59, v219, v59, vcc
	v_cmp_gt_u32_e32 vcc, s60, v47
	v_subrev_u32_e32 v47, 20, v157
	s_nop 0
	v_cndmask_b32_e32 v58, v219, v58, vcc
	v_cmp_gt_u32_e32 vcc, s61, v46
	v_subrev_u32_e32 v46, 23, v157
	s_nop 0
	v_cndmask_b32_e32 v43, v219, v43, vcc
	v_cmp_gt_u32_e32 vcc, s60, v47
	v_subrev_u32_e32 v47, 22, v157
	s_nop 0
	v_cndmask_b32_e32 v42, v219, v42, vcc
	v_cmp_gt_u32_e32 vcc, s61, v46
	v_subrev_u32_e32 v46, 33, v157
	s_nop 0
	v_cndmask_b32_e32 v45, v219, v45, vcc
	v_cmp_gt_u32_e32 vcc, s60, v47
	v_subrev_u32_e32 v47, 32, v157
	s_nop 0
	v_cndmask_b32_e32 v44, v219, v44, vcc
	v_cmp_gt_u32_e32 vcc, s61, v46
	v_subrev_u32_e32 v46, 35, v157
	s_nop 0
	v_cndmask_b32_e32 v117, v219, v117, vcc
	v_cmp_gt_u32_e32 vcc, s60, v47
	v_subrev_u32_e32 v47, 34, v157
	s_nop 0
	v_cndmask_b32_e32 v116, v219, v116, vcc
	v_cmp_gt_u32_e32 vcc, s61, v46
	v_subrev_u32_e32 v46, 37, v157
	s_nop 0
	v_cndmask_b32_e32 v51, v219, v51, vcc
	v_cmp_gt_u32_e32 vcc, s60, v47
	v_subrev_u32_e32 v47, 36, v157
	s_nop 0
	v_cndmask_b32_e32 v50, v219, v50, vcc
	v_cmp_gt_u32_e32 vcc, s61, v46
	v_subrev_u32_e32 v46, 39, v157
	s_nop 0
	v_cndmask_b32_e32 v49, v219, v49, vcc
	v_cmp_gt_u32_e32 vcc, s60, v47
	v_subrev_u32_e32 v47, 38, v157
	s_nop 0
	v_cndmask_b32_e32 v48, v219, v48, vcc
	v_cmp_gt_u32_e32 vcc, s61, v46
	v_subrev_u32_e32 v46, 49, v157
	s_nop 0
	v_cndmask_b32_e32 v35, v219, v35, vcc
	v_cmp_gt_u32_e32 vcc, s60, v47
	v_subrev_u32_e32 v47, 48, v157
	s_nop 0
	v_cndmask_b32_e32 v34, v219, v34, vcc
	v_cmp_gt_u32_e32 vcc, s61, v46
	v_subrev_u32_e32 v46, 51, v157
	s_nop 0
	v_cndmask_b32_e32 v37, v219, v37, vcc
	v_cmp_gt_u32_e32 vcc, s60, v47
	v_subrev_u32_e32 v47, 50, v157
	s_nop 0
	v_cndmask_b32_e32 v36, v219, v36, vcc
	v_cmp_gt_u32_e32 vcc, s61, v46
	v_subrev_u32_e32 v46, 53, v157
	s_nop 0
	v_cndmask_b32_e32 v39, v219, v39, vcc
	v_cmp_gt_u32_e32 vcc, s60, v47
	v_subrev_u32_e32 v47, 52, v157
	s_nop 0
	v_cndmask_b32_e32 v38, v219, v38, vcc
	v_cmp_gt_u32_e32 vcc, s61, v46
	v_subrev_u32_e32 v46, 55, v157
	s_nop 0
	v_cndmask_b32_e32 v41, v219, v41, vcc
	v_cmp_gt_u32_e32 vcc, s60, v47
	v_subrev_u32_e32 v47, 54, v157
	s_nop 0
	v_cndmask_b32_e32 v40, v219, v40, vcc
	v_cmp_gt_u32_e32 vcc, s61, v46
	s_nop 1
	v_cndmask_b32_e32 v33, v219, v33, vcc
	v_cmp_gt_u32_e32 vcc, s60, v47
	s_nop 1
	v_cndmask_b32_e32 v32, v219, v32, vcc
